# XCD grid barrier: released workgroups poll the cross-XCC generation word directly (leader re-publish hop and XGEN add removed), on top of v11
# speedup vs baseline: 1.0057x; 1.0057x over previous
.LBB0_606:
	s_or_b64 exec, exec, s[4:5]
	v_cvt_f32_u32_e32 v4, v2
	s_waitcnt vmcnt(0)
	v_readfirstlane_b32 s2, v3
	v_sub_u32_e32 v3, 0, v2
	v_rcp_iflag_f32_e32 v4, v4
	v_add_u32_e32 v5, s2, v1
	v_mul_f32_e32 v4, 0x4f7ffffe, v4
	v_cvt_u32_f32_e32 v4, v4
	v_mul_lo_u32 v1, v3, v4
	v_mul_hi_u32 v1, v4, v1
	v_add_u32_e32 v1, v4, v1
	v_mul_hi_u32 v1, v5, v1
	v_mul_lo_u32 v3, v1, v2
	v_sub_u32_e32 v3, v5, v3
	v_add_u32_e32 v4, 1, v1
	v_cmp_ge_u32_e32 vcc, v3, v2
	s_nop 1
	v_cndmask_b32_e32 v1, v1, v4, vcc
	v_sub_u32_e32 v4, v3, v2
	v_cndmask_b32_e32 v3, v3, v4, vcc
	v_add_u32_e32 v4, 1, v1
	v_cmp_ge_u32_e32 vcc, v3, v2
	v_add_u32_e32 v3, 1, v5
	s_nop 0
	v_cndmask_b32_e32 v1, v1, v4, vcc
	v_mul_lo_u32 v4, v2, v1
	v_add_u32_e32 v2, v4, v2
	v_cmp_ne_u32_e32 vcc, v3, v2
	s_and_saveexec_b64 s[2:3], vcc
	s_xor_b64 s[4:5], exec, s[2:3]
	s_cbranch_execz .LBB0_620
	v_readlane_b32 s2, v246, 55
	v_readlane_b32 s3, v246, 56
	s_waitcnt lgkmcnt(0)
	s_nop 3
	global_load_dword v0, v155, s[2:3] sc1
	s_waitcnt vmcnt(0)
	v_cmp_eq_u32_e32 vcc, v0, v1
	s_and_saveexec_b64 s[6:7], vcc
	s_cbranch_execz .LBB0_619
	s_mov_b32 s2, 1
	s_mov_b64 s[8:9], 0
	s_branch .LBB0_610

.LBB0_612:
	v_readlane_b32 s12, v246, 55
	v_readlane_b32 s13, v246, 56
	s_add_i32 s2, s2, 1
	s_mov_b64 s[20:21], -1
	s_nop 2
	global_load_dword v0, v155, s[12:13] sc1
	s_waitcnt vmcnt(0)
	v_cmp_ne_u32_e32 vcc, v0, v1
	s_orn2_b64 s[16:17], vcc, exec
	s_branch .LBB0_609

.LBB0_637:
	s_or_b64 exec, exec, s[4:5]
	s_mov_b64 s[4:5], exec
	v_mbcnt_lo_u32_b32 v0, s4, 0
	v_mbcnt_hi_u32_b32 v0, s5, v0
	v_cmp_eq_u32_e32 vcc, 0, v0
	s_waitcnt vmcnt(0)
	buffer_inv sc1
	s_and_saveexec_b64 s[6:7], vcc
	s_cbranch_execz .LBB0_639
	s_bcnt1_i32_b64 s2, s[4:5]
	v_mov_b32_e32 v0, s2
.LBB0_639:
	s_or_b64 exec, exec, s[6:7]
	s_waitcnt vmcnt(0)
